# ret_scan per-step wait counts the interleaved state stores too (vmcnt 20 from step 5): the 5-step LDS-DMA prefetch is no longer cut to ~2 steps - on top of v63
# baseline (speedup 1.0000x reference)
.LBB0_1739:
	s_min_u32 s10, s17, 0x7a
	s_add_i32 s10, s10, 5
	s_mul_i32 s18, s10, 0xab
	s_lshr_b32 s18, s18, 10
	s_mul_i32 s18, s18, 6
	s_sub_i32 s18, s10, s18
	s_and_b32 s18, s18, 0xff
	s_mulk_i32 s18, 0x6000
	s_cmp_lt_u32 s17, 5
	s_cbranch_scc1 .Lmy_scan_w12
	s_waitcnt vmcnt(20)
	s_branch .Lmy_scan_wd
.Lmy_scan_w12:
	s_waitcnt vmcnt(12)
.Lmy_scan_wd:
	s_add_i32 s18, s18, 0
	s_lshl_b32 s10, s10, 7
	s_barrier
	s_add_i32 m0, s18, s0
	v_lshl_add_u64 v[50:51], v[34:35], 0, s[10:11]
	global_load_lds_dwordx4 v[50:51], off
	s_add_i32 m0, s18, s2
	v_lshl_add_u64 v[50:51], v[36:37], 0, s[10:11]
	global_load_lds_dwordx4 v[50:51], off
	v_lshl_add_u64 v[50:51], v[38:39], 0, s[10:11]
	s_add_i32 m0, s18, s3
	s_bitcmp1_b32 s17, 0
	global_load_lds_dwordx4 v[50:51], off
	s_cselect_b64 s[18:19], -1, 0
	s_and_b64 vcc, exec, s[18:19]
	s_cbranch_vccnz .LBB0_1738
	v_cvt_pk_f16_f32 v50, v4, v5
	v_cvt_pk_f16_f32 v51, v6, v7
	v_add_co_u32_e32 v52, vcc, s26, v42
	global_store_dwordx2 v[42:43], v[50:51], off
	v_cvt_pk_f16_f32 v50, v12, v13
	v_cvt_pk_f16_f32 v51, v14, v15
	v_addc_co_u32_e32 v53, vcc, 0, v43, vcc
	global_store_dwordx2 v[52:53], v[50:51], off
	v_add_co_u32_e32 v52, vcc, s22, v42
	v_cvt_pk_f16_f32 v50, v8, v9
	v_cvt_pk_f16_f32 v51, v10, v11
	v_addc_co_u32_e32 v53, vcc, 0, v43, vcc
	global_store_dwordx2 v[52:53], v[50:51], off
	v_add_co_u32_e32 v52, vcc, s23, v42
	v_mov_b32_e32 v33, v32
	v_cvt_pk_f16_f32 v50, v0, v1
	v_cvt_pk_f16_f32 v51, v2, v3
	v_addc_co_u32_e32 v53, vcc, 0, v43, vcc
	v_pk_mul_f32 v[2:3], v[32:33], v[2:3]
	v_pk_mul_f32 v[0:1], v[32:33], v[0:1]
	v_pk_mul_f32 v[10:11], v[32:33], v[10:11]
	v_pk_mul_f32 v[8:9], v[32:33], v[8:9]
	v_pk_mul_f32 v[14:15], v[32:33], v[14:15]
	v_pk_mul_f32 v[12:13], v[32:33], v[12:13]
	v_pk_mul_f32 v[6:7], v[32:33], v[6:7]
	v_pk_mul_f32 v[4:5], v[40:41], v[4:5]
	global_store_dwordx2 v[52:53], v[50:51], off
	s_branch .LBB0_1738
